# v20 plus accumulator zeroing with 64 v_mov_b64 instead of 128 v_mov_b32 per GEMM unit
# speedup vs baseline: 1.0086x; 1.0026x over previous
.LBB0_245:
	s_ashr_i32 s69, s68, 31
	s_lshl_b64 s[56:57], s[68:69], 20
	s_add_u32 s33, s14, s56
	s_addc_u32 s48, s15, s57
	s_ashr_i32 s75, s74, 31
	s_lshl_b64 s[56:57], s[74:75], 7
	s_add_u32 s84, s33, s56
	s_addc_u32 s85, s48, s57
	s_and_b64 s[76:77], s[90:91], exec
	s_cselect_b32 s69, s85, s1
	s_cselect_b32 s75, s84, s0
	s_ashr_i32 s73, s72, 31
	s_lshl_b64 s[76:77], s[72:73], 20
	s_add_u32 s33, s9, s76
	s_addc_u32 s48, s23, s77
	s_add_u32 s86, s33, s56
	s_addc_u32 s87, s48, s57
	s_and_b64 s[56:57], s[90:91], exec
	s_cselect_b32 s73, s87, s89
	s_cselect_b32 vcc_lo, s86, s88
	s_add_i32 vcc_hi, s55, -2
	s_add_u32 s0, s0, 0x80080
	s_addc_u32 s1, s1, 0
	s_add_u32 s56, s88, 0x100
	s_addc_u32 s57, s89, 0
	s_mov_b32 s88, 0
	v_mov_b64_e32 v[4:5], 0
	v_mov_b64_e32 v[6:7], 0
	v_mov_b64_e32 v[8:9], 0
	v_mov_b64_e32 v[10:11], 0
	v_mov_b64_e32 v[12:13], 0
	v_mov_b64_e32 v[14:15], 0
	v_mov_b64_e32 v[16:17], 0
	v_mov_b64_e32 v[18:19], 0
	v_mov_b64_e32 v[20:21], 0
	v_mov_b64_e32 v[22:23], 0
	v_mov_b64_e32 v[24:25], 0
	v_mov_b64_e32 v[26:27], 0
	v_mov_b64_e32 v[28:29], 0
	v_mov_b64_e32 v[30:31], 0
	v_mov_b64_e32 v[32:33], 0
	v_mov_b64_e32 v[34:35], 0
	v_mov_b64_e32 v[36:37], 0
	v_mov_b64_e32 v[38:39], 0
	v_mov_b64_e32 v[40:41], 0
	v_mov_b64_e32 v[42:43], 0
	v_mov_b64_e32 v[44:45], 0
	v_mov_b64_e32 v[46:47], 0
	v_mov_b64_e32 v[48:49], 0
	v_mov_b64_e32 v[50:51], 0
	v_mov_b64_e32 v[52:53], 0
	v_mov_b64_e32 v[54:55], 0
	v_mov_b64_e32 v[56:57], 0
	v_mov_b64_e32 v[58:59], 0
	v_mov_b64_e32 v[60:61], 0
	v_mov_b64_e32 v[62:63], 0
	v_mov_b64_e32 v[64:65], 0
	v_mov_b64_e32 v[66:67], 0
	v_mov_b64_e32 v[68:69], 0
	v_mov_b64_e32 v[70:71], 0
	v_mov_b64_e32 v[72:73], 0
	v_mov_b64_e32 v[74:75], 0
	v_mov_b64_e32 v[76:77], 0
	v_mov_b64_e32 v[78:79], 0
	v_mov_b64_e32 v[80:81], 0
	v_mov_b64_e32 v[82:83], 0
	v_mov_b64_e32 v[84:85], 0
	v_mov_b64_e32 v[86:87], 0
	v_mov_b64_e32 v[88:89], 0
	v_mov_b64_e32 v[90:91], 0
	v_mov_b64_e32 v[92:93], 0
	v_mov_b64_e32 v[94:95], 0
	v_mov_b64_e32 v[96:97], 0
	v_mov_b64_e32 v[98:99], 0
	v_mov_b64_e32 v[100:101], 0
	v_mov_b64_e32 v[102:103], 0
	v_mov_b64_e32 v[104:105], 0
	v_mov_b64_e32 v[106:107], 0
	v_mov_b64_e32 v[108:109], 0
	v_mov_b64_e32 v[110:111], 0
	v_mov_b64_e32 v[112:113], 0
	v_mov_b64_e32 v[114:115], 0
	v_mov_b64_e32 v[116:117], 0
	v_mov_b64_e32 v[118:119], 0
	v_mov_b64_e32 v[120:121], 0
	v_mov_b64_e32 v[122:123], 0
	v_mov_b64_e32 v[124:125], 0
	v_mov_b64_e32 v[126:127], 0
	v_mov_b64_e32 v[128:129], 0
	v_mov_b64_e32 v[130:131], 0

.LBB0_520:
	s_add_i32 s9, s64, -2
	s_add_u32 s74, s74, 0x80080
	s_addc_u32 s75, s75, 0
	s_add_u32 s23, s84, 0x100
	s_addc_u32 s35, s85, 0
	s_mov_b32 s54, 0
	v_mov_b64_e32 v[4:5], 0
	v_mov_b64_e32 v[6:7], 0
	v_mov_b64_e32 v[8:9], 0
	v_mov_b64_e32 v[10:11], 0
	v_mov_b64_e32 v[12:13], 0
	v_mov_b64_e32 v[14:15], 0
	v_mov_b64_e32 v[16:17], 0
	v_mov_b64_e32 v[18:19], 0
	v_mov_b64_e32 v[20:21], 0
	v_mov_b64_e32 v[22:23], 0
	v_mov_b64_e32 v[24:25], 0
	v_mov_b64_e32 v[26:27], 0
	v_mov_b64_e32 v[28:29], 0
	v_mov_b64_e32 v[30:31], 0
	v_mov_b64_e32 v[32:33], 0
	v_mov_b64_e32 v[34:35], 0
	v_mov_b64_e32 v[36:37], 0
	v_mov_b64_e32 v[38:39], 0
	v_mov_b64_e32 v[40:41], 0
	v_mov_b64_e32 v[42:43], 0
	v_mov_b64_e32 v[44:45], 0
	v_mov_b64_e32 v[46:47], 0
	v_mov_b64_e32 v[48:49], 0
	v_mov_b64_e32 v[50:51], 0
	v_mov_b64_e32 v[52:53], 0
	v_mov_b64_e32 v[54:55], 0
	v_mov_b64_e32 v[56:57], 0
	v_mov_b64_e32 v[58:59], 0
	v_mov_b64_e32 v[60:61], 0
	v_mov_b64_e32 v[62:63], 0
	v_mov_b64_e32 v[64:65], 0
	v_mov_b64_e32 v[66:67], 0
	v_mov_b64_e32 v[68:69], 0
	v_mov_b64_e32 v[70:71], 0
	v_mov_b64_e32 v[72:73], 0
	v_mov_b64_e32 v[74:75], 0
	v_mov_b64_e32 v[76:77], 0
	v_mov_b64_e32 v[78:79], 0
	v_mov_b64_e32 v[80:81], 0
	v_mov_b64_e32 v[82:83], 0
	v_mov_b64_e32 v[84:85], 0
	v_mov_b64_e32 v[86:87], 0
	v_mov_b64_e32 v[88:89], 0
	v_mov_b64_e32 v[90:91], 0
	v_mov_b64_e32 v[92:93], 0
	v_mov_b64_e32 v[94:95], 0
	v_mov_b64_e32 v[96:97], 0
	v_mov_b64_e32 v[98:99], 0
	v_mov_b64_e32 v[100:101], 0
	v_mov_b64_e32 v[102:103], 0
	v_mov_b64_e32 v[104:105], 0
	v_mov_b64_e32 v[106:107], 0
	v_mov_b64_e32 v[108:109], 0
	v_mov_b64_e32 v[110:111], 0
	v_mov_b64_e32 v[112:113], 0
	v_mov_b64_e32 v[114:115], 0
	v_mov_b64_e32 v[116:117], 0
	v_mov_b64_e32 v[118:119], 0
	v_mov_b64_e32 v[120:121], 0
	v_mov_b64_e32 v[122:123], 0
	v_mov_b64_e32 v[124:125], 0
	v_mov_b64_e32 v[126:127], 0
	v_mov_b64_e32 v[128:129], 0
	v_mov_b64_e32 v[130:131], 0

.LBB0_693:
	s_ashr_i32 s75, s74, 31
	s_lshl_b64 s[16:17], s[74:75], 20
	s_add_u32 s84, s14, s16
	s_addc_u32 s85, s15, s17
	s_and_b64 s[16:17], s[36:37], exec
	s_cselect_b32 s16, s85, s89
	s_cselect_b32 s17, s84, s88
	s_ashr_i32 s73, s72, 31
	s_lshl_b64 s[50:51], s[72:73], 20
	s_add_u32 s86, s23, s50
	s_addc_u32 s87, s29, s51
	s_and_b64 s[50:51], s[36:37], exec
	s_cselect_b32 s50, s87, s91
	s_cselect_b32 s51, s86, s90
	s_add_u32 s88, s88, 0x80080
	s_addc_u32 s89, s89, 0
	s_add_u32 s54, s90, 0x100
	s_addc_u32 s55, s91, 0
	s_mov_b32 s56, -2
	v_mov_b64_e32 v[4:5], 0
	v_mov_b64_e32 v[6:7], 0
	v_mov_b64_e32 v[8:9], 0
	v_mov_b64_e32 v[10:11], 0
	v_mov_b64_e32 v[12:13], 0
	v_mov_b64_e32 v[14:15], 0
	v_mov_b64_e32 v[16:17], 0
	v_mov_b64_e32 v[18:19], 0
	v_mov_b64_e32 v[20:21], 0
	v_mov_b64_e32 v[22:23], 0
	v_mov_b64_e32 v[24:25], 0
	v_mov_b64_e32 v[26:27], 0
	v_mov_b64_e32 v[28:29], 0
	v_mov_b64_e32 v[30:31], 0
	v_mov_b64_e32 v[32:33], 0
	v_mov_b64_e32 v[34:35], 0
	v_mov_b64_e32 v[36:37], 0
	v_mov_b64_e32 v[38:39], 0
	v_mov_b64_e32 v[40:41], 0
	v_mov_b64_e32 v[42:43], 0
	v_mov_b64_e32 v[44:45], 0
	v_mov_b64_e32 v[46:47], 0
	v_mov_b64_e32 v[48:49], 0
	v_mov_b64_e32 v[50:51], 0
	v_mov_b64_e32 v[52:53], 0
	v_mov_b64_e32 v[54:55], 0
	v_mov_b64_e32 v[56:57], 0
	v_mov_b64_e32 v[58:59], 0
	v_mov_b64_e32 v[60:61], 0
	v_mov_b64_e32 v[62:63], 0
	v_mov_b64_e32 v[64:65], 0
	v_mov_b64_e32 v[66:67], 0
	v_mov_b64_e32 v[68:69], 0
	v_mov_b64_e32 v[70:71], 0
	v_mov_b64_e32 v[72:73], 0
	v_mov_b64_e32 v[74:75], 0
	v_mov_b64_e32 v[76:77], 0
	v_mov_b64_e32 v[78:79], 0
	v_mov_b64_e32 v[80:81], 0
	v_mov_b64_e32 v[82:83], 0
	v_mov_b64_e32 v[84:85], 0
	v_mov_b64_e32 v[86:87], 0
	v_mov_b64_e32 v[88:89], 0
	v_mov_b64_e32 v[90:91], 0
	v_mov_b64_e32 v[92:93], 0
	v_mov_b64_e32 v[94:95], 0
	v_mov_b64_e32 v[96:97], 0
	v_mov_b64_e32 v[98:99], 0
	v_mov_b64_e32 v[100:101], 0
	v_mov_b64_e32 v[102:103], 0
	v_mov_b64_e32 v[104:105], 0
	v_mov_b64_e32 v[106:107], 0
	v_mov_b64_e32 v[108:109], 0
	v_mov_b64_e32 v[110:111], 0
	v_mov_b64_e32 v[112:113], 0
	v_mov_b64_e32 v[114:115], 0
	v_mov_b64_e32 v[116:117], 0
	v_mov_b64_e32 v[118:119], 0
	v_mov_b64_e32 v[120:121], 0
	v_mov_b64_e32 v[122:123], 0
	v_mov_b64_e32 v[124:125], 0
	v_mov_b64_e32 v[126:127], 0
	v_mov_b64_e32 v[128:129], 0
	v_mov_b64_e32 v[130:131], 0

.LBB0_762:
	s_add_i32 s23, s51, -2
	s_add_u32 s84, s84, 0x200080
	s_addc_u32 s85, s85, 0
	s_add_u32 s29, s86, 0x100
	s_addc_u32 s35, s87, 0
	s_mov_b32 s55, 0
	v_mov_b64_e32 v[4:5], 0
	v_mov_b64_e32 v[6:7], 0
	v_mov_b64_e32 v[8:9], 0
	v_mov_b64_e32 v[10:11], 0
	v_mov_b64_e32 v[12:13], 0
	v_mov_b64_e32 v[14:15], 0
	v_mov_b64_e32 v[16:17], 0
	v_mov_b64_e32 v[18:19], 0
	v_mov_b64_e32 v[20:21], 0
	v_mov_b64_e32 v[22:23], 0
	v_mov_b64_e32 v[24:25], 0
	v_mov_b64_e32 v[26:27], 0
	v_mov_b64_e32 v[28:29], 0
	v_mov_b64_e32 v[30:31], 0
	v_mov_b64_e32 v[32:33], 0
	v_mov_b64_e32 v[34:35], 0
	v_mov_b64_e32 v[36:37], 0
	v_mov_b64_e32 v[38:39], 0
	v_mov_b64_e32 v[40:41], 0
	v_mov_b64_e32 v[42:43], 0
	v_mov_b64_e32 v[44:45], 0
	v_mov_b64_e32 v[46:47], 0
	v_mov_b64_e32 v[48:49], 0
	v_mov_b64_e32 v[50:51], 0
	v_mov_b64_e32 v[52:53], 0
	v_mov_b64_e32 v[54:55], 0
	v_mov_b64_e32 v[56:57], 0
	v_mov_b64_e32 v[58:59], 0
	v_mov_b64_e32 v[60:61], 0
	v_mov_b64_e32 v[62:63], 0
	v_mov_b64_e32 v[64:65], 0
	v_mov_b64_e32 v[66:67], 0
	v_mov_b64_e32 v[68:69], 0
	v_mov_b64_e32 v[70:71], 0
	v_mov_b64_e32 v[72:73], 0
	v_mov_b64_e32 v[74:75], 0
	v_mov_b64_e32 v[76:77], 0
	v_mov_b64_e32 v[78:79], 0
	v_mov_b64_e32 v[80:81], 0
	v_mov_b64_e32 v[82:83], 0
	v_mov_b64_e32 v[84:85], 0
	v_mov_b64_e32 v[86:87], 0
	v_mov_b64_e32 v[88:89], 0
	v_mov_b64_e32 v[90:91], 0
	v_mov_b64_e32 v[92:93], 0
	v_mov_b64_e32 v[94:95], 0
	v_mov_b64_e32 v[96:97], 0
	v_mov_b64_e32 v[98:99], 0
	v_mov_b64_e32 v[100:101], 0
	v_mov_b64_e32 v[102:103], 0
	v_mov_b64_e32 v[104:105], 0
	v_mov_b64_e32 v[106:107], 0
	v_mov_b64_e32 v[108:109], 0
	v_mov_b64_e32 v[110:111], 0
	v_mov_b64_e32 v[112:113], 0
	v_mov_b64_e32 v[114:115], 0
	v_mov_b64_e32 v[116:117], 0
	v_mov_b64_e32 v[118:119], 0
	v_mov_b64_e32 v[120:121], 0
	v_mov_b64_e32 v[122:123], 0
	v_mov_b64_e32 v[124:125], 0
	v_mov_b64_e32 v[126:127], 0
	v_mov_b64_e32 v[128:129], 0
	v_mov_b64_e32 v[130:131], 0
